# hgrn_sample_unit: v / gate / norm-weight loads issued together with the state loads (three serial round trips per unit become one; tail no longer waits for the state stores)
# speedup vs baseline: 1.0305x; 1.0305x over previous
.LBB0_323:
	s_ashr_i32 s10, s16, 2
	s_add_i32 s6, s10, 0x4000
	s_and_b32 s7, s16, 3
	s_mul_i32 s0, s6, 0xc00
	v_mov_b32_e32 v5, v176
	s_mul_hi_i32 s1, s6, 0xc00
	s_add_u32 s0, s82, s0
	s_addc_u32 s1, s83, s1
	v_and_b32_e32 v3, 0x7f, v5
	s_lshl_b32 s12, s7, 7
	s_mul_i32 s8, s6, 0x2600
	s_mul_hi_i32 s9, s6, 0x2600
	s_add_u32 s8, s80, s8
	v_or_b32_e32 v0, s12, v3
	s_addc_u32 s9, s81, s9
	v_lshlrev_b32_e32 v4, 1, v0
	global_load_ushort v8, v4, s[8:9]
	global_load_ushort v40, v4, s[8:9] offset:1024
	v_readlane_b32 s44, v254, 59
	v_mov_b32_e32 v41, s44
	ds_read_b64 v[50:51], v41
	s_waitcnt lgkmcnt(0)
	v_readfirstlane_b32 s44, v50
	v_readfirstlane_b32 s45, v51
	s_add_u32 s44, s44, s4
	s_addc_u32 s45, s45, s5
	s_lshl_b32 s46, s12, 2
	s_add_u32 s44, s44, s46
	s_addc_u32 s45, s45, 0
	v_lshlrev_b32_e32 v41, 2, v3
	global_load_dword v41, v41, s[44:45]
	v_readlane_b32 s11, v254, 63
	v_ashrrev_i32_e32 v10, 2, v5
	v_and_b32_e32 v6, 0xffffffe0, v10
	v_ashrrev_i32_e32 v7, 31, v6
	v_lshlrev_b64 v[12:13], 9, v[6:7]
	v_mov_b32_e32 v0, s11
	ds_read_b64 v[0:1], v0
	s_ashr_i32 s11, s10, 31
	s_lshl_b64 s[10:11], s[10:11], 2
	s_add_u32 s10, s10, s2
	s_addc_u32 s11, s11, s3
	s_or_b32 s10, s10, s7
	s_waitcnt lgkmcnt(0)
	v_readfirstlane_b32 s13, v0
	s_lshl_b64 s[10:11], s[10:11], 16
	v_readfirstlane_b32 s15, v1
	s_add_u32 s14, s13, s10
	s_addc_u32 s15, s15, s11
	v_readlane_b32 s13, v253, 16
	v_lshl_add_u64 v[14:15], s[14:15], 0, v[12:13]
	v_lshlrev_b32_e32 v0, 2, v3
	v_mov_b32_e32 v1, v2
	s_add_u32 s10, s13, s10
	v_readlane_b32 s13, v253, 17
	v_lshl_add_u64 v[34:35], v[14:15], 0, v[0:1]
	s_addc_u32 s11, s13, s11
	v_lshl_add_u64 v[36:37], s[10:11], 0, v[12:13]
	v_add_co_u32_e32 v12, vcc, s20, v34
	s_lshl_b32 s10, s7, 9
	s_nop 0
	v_addc_co_u32_e32 v13, vcc, 0, v35, vcc
	v_add_co_u32_e32 v38, vcc, s95, v34
	flat_load_dword v32, v[34:35] nt
	flat_load_dword v42, v[34:35] offset:512 nt
	flat_load_dword v43, v[34:35] offset:1024 nt
	flat_load_dword v44, v[34:35] offset:1536 nt
	flat_load_dword v45, v[34:35] offset:2048 nt
	flat_load_dword v46, v[34:35] offset:2560 nt
	flat_load_dword v47, v[34:35] offset:3072 nt
	flat_load_dword v48, v[34:35] offset:3584 nt
	v_addc_co_u32_e32 v39, vcc, 0, v35, vcc
	v_add_co_u32_e32 v34, vcc, s78, v34
	s_add_u32 s0, s0, s10
	s_nop 0
	v_addc_co_u32_e32 v35, vcc, 0, v35, vcc
	s_addc_u32 s1, s1, 0
	flat_load_dword v49, v[12:13] nt
	flat_load_dword v30, v[12:13] offset:512 nt
	flat_load_dword v28, v[12:13] offset:1024 nt
	flat_load_dword v26, v[12:13] offset:1536 nt
	flat_load_dword v24, v[12:13] offset:2048 nt
	flat_load_dword v22, v[12:13] offset:2560 nt
	flat_load_dword v20, v[12:13] offset:3072 nt
	flat_load_dword v18, v[12:13] offset:3584 nt
	flat_load_dword v16, v[38:39] nt
	flat_load_dword v14, v[38:39] offset:512 nt
	s_nop 0
	flat_load_dword v12, v[38:39] offset:1024 nt
	flat_load_dword v9, v[38:39] offset:1536 nt
	flat_load_dword v33, v[38:39] offset:2048 nt
	flat_load_dword v31, v[38:39] offset:2560 nt
	flat_load_dword v29, v[38:39] offset:3072 nt
	flat_load_dword v27, v[38:39] offset:3584 nt
	flat_load_dword v25, v[34:35] nt
	flat_load_dword v23, v[34:35] offset:512 nt
	flat_load_dword v21, v[34:35] offset:1024 nt
	flat_load_dword v19, v[34:35] offset:1536 nt
	flat_load_dword v17, v[34:35] offset:2048 nt
	flat_load_dword v15, v[34:35] offset:2560 nt
	flat_load_dword v13, v[34:35] offset:3072 nt
	flat_load_dword v11, v[34:35] offset:3584 nt
	v_lshl_add_u64 v[34:35], v[6:7], 2, s[0:1]
	v_lshl_add_u64 v[36:37], v[36:37], 0, v[0:1]
	global_load_dwordx4 v[96:99], v[34:35], off
	global_load_dwordx4 v[100:103], v[34:35], off offset:16
	global_load_dwordx4 v[104:107], v[34:35], off offset:32
	global_load_dwordx4 v[108:111], v[34:35], off offset:48
	global_load_dwordx4 v[112:115], v[34:35], off offset:64
	global_load_dwordx4 v[116:119], v[34:35], off offset:80
	global_load_dwordx4 v[120:123], v[34:35], off offset:96
	global_load_dwordx4 v[124:127], v[34:35], off offset:112
	s_lshl_b32 s7, s7, 8
	s_sub_u32 s7, 0, s7
	s_subb_u32 s11, 0, 0
	s_add_u32 s10, s0, s7
	s_addc_u32 s11, s1, s11
	v_lshl_add_u64 v[6:7], v[6:7], 1, s[10:11]
	global_load_dwordx4 v[128:131], v[6:7], off offset:2048
	global_load_dwordx4 v[132:135], v[6:7], off offset:2064
	global_load_dwordx4 v[136:139], v[6:7], off offset:2080
	global_load_dwordx4 v[140:143], v[6:7], off offset:2096
	v_add_co_u32_e32 v52, vcc, s20, v36
	s_nop 1
	v_addc_co_u32_e32 v53, vcc, 0, v37, vcc
	v_add_co_u32_e32 v54, vcc, s95, v36
	s_nop 1
	v_addc_co_u32_e32 v55, vcc, 0, v37, vcc
	v_add_co_u32_e32 v56, vcc, s78, v36
	s_nop 1
	v_addc_co_u32_e32 v57, vcc, 0, v37, vcc
	s_waitcnt vmcnt(0) lgkmcnt(0)
	v_lshlrev_b32_e32 v8, 16, v8
	v_sub_f32_e32 v58, 1.0, v96
	v_mul_f32_e32 v32, v32, v58
	v_fmac_f32_e32 v32, v96, v8
	global_store_dword v[36:37], v32, off nt
	v_lshlrev_b32_e32 v59, 16, v128
	v_mul_f32_e32 v1, v32, v59
	v_sub_f32_e32 v60, 1.0, v97
	v_mul_f32_e32 v42, v42, v60
	v_fmac_f32_e32 v42, v97, v8
	global_store_dword v[36:37], v42, off offset:512 nt
	v_and_b32_e32 v61, 0xffff0000, v128
	v_fmac_f32_e32 v1, v42, v61
	v_sub_f32_e32 v58, 1.0, v98
	v_mul_f32_e32 v43, v43, v58
	v_fmac_f32_e32 v43, v98, v8
	global_store_dword v[36:37], v43, off offset:1024 nt
	v_lshlrev_b32_e32 v59, 16, v129
	v_fmac_f32_e32 v1, v43, v59
	v_sub_f32_e32 v60, 1.0, v99
	v_mul_f32_e32 v44, v44, v60
	v_fmac_f32_e32 v44, v99, v8
	global_store_dword v[36:37], v44, off offset:1536 nt
	v_and_b32_e32 v61, 0xffff0000, v129
	v_fmac_f32_e32 v1, v44, v61
	v_sub_f32_e32 v58, 1.0, v100
	v_mul_f32_e32 v45, v45, v58
	v_fmac_f32_e32 v45, v100, v8
	global_store_dword v[36:37], v45, off offset:2048 nt
	v_lshlrev_b32_e32 v59, 16, v130
	v_fmac_f32_e32 v1, v45, v59
	v_sub_f32_e32 v60, 1.0, v101
	v_mul_f32_e32 v46, v46, v60
	v_fmac_f32_e32 v46, v101, v8
	global_store_dword v[36:37], v46, off offset:2560 nt
	v_and_b32_e32 v61, 0xffff0000, v130
	v_fmac_f32_e32 v1, v46, v61
	v_sub_f32_e32 v58, 1.0, v102
	v_mul_f32_e32 v47, v47, v58
	v_fmac_f32_e32 v47, v102, v8
	global_store_dword v[36:37], v47, off offset:3072 nt
	v_lshlrev_b32_e32 v59, 16, v131
	v_fmac_f32_e32 v1, v47, v59
	v_sub_f32_e32 v60, 1.0, v103
	v_mul_f32_e32 v48, v48, v60
	v_fmac_f32_e32 v48, v103, v8
	global_store_dword v[36:37], v48, off offset:3584 nt
	v_and_b32_e32 v61, 0xffff0000, v131
	v_fmac_f32_e32 v1, v48, v61
	v_sub_f32_e32 v58, 1.0, v104
	v_mul_f32_e32 v49, v49, v58
	v_fmac_f32_e32 v49, v104, v8
	global_store_dword v[52:53], v49, off nt
	v_lshlrev_b32_e32 v59, 16, v132
	v_fmac_f32_e32 v1, v49, v59
	v_sub_f32_e32 v60, 1.0, v105
	v_mul_f32_e32 v30, v30, v60
	v_fmac_f32_e32 v30, v105, v8
	global_store_dword v[52:53], v30, off offset:512 nt
	v_and_b32_e32 v61, 0xffff0000, v132
	v_fmac_f32_e32 v1, v30, v61
	v_sub_f32_e32 v58, 1.0, v106
	v_mul_f32_e32 v28, v28, v58
	v_fmac_f32_e32 v28, v106, v8
	global_store_dword v[52:53], v28, off offset:1024 nt
	v_lshlrev_b32_e32 v59, 16, v133
	v_fmac_f32_e32 v1, v28, v59
	v_sub_f32_e32 v60, 1.0, v107
	v_mul_f32_e32 v26, v26, v60
	v_fmac_f32_e32 v26, v107, v8
	global_store_dword v[52:53], v26, off offset:1536 nt
	v_and_b32_e32 v61, 0xffff0000, v133
	v_fmac_f32_e32 v1, v26, v61
	v_sub_f32_e32 v58, 1.0, v108
	v_mul_f32_e32 v24, v24, v58
	v_fmac_f32_e32 v24, v108, v8
	global_store_dword v[52:53], v24, off offset:2048 nt
	v_lshlrev_b32_e32 v59, 16, v134
	v_fmac_f32_e32 v1, v24, v59
	v_sub_f32_e32 v60, 1.0, v109
	v_mul_f32_e32 v22, v22, v60
	v_fmac_f32_e32 v22, v109, v8
	global_store_dword v[52:53], v22, off offset:2560 nt
	v_and_b32_e32 v61, 0xffff0000, v134
	v_fmac_f32_e32 v1, v22, v61
	v_sub_f32_e32 v58, 1.0, v110
	v_mul_f32_e32 v20, v20, v58
	v_fmac_f32_e32 v20, v110, v8
	global_store_dword v[52:53], v20, off offset:3072 nt
	v_lshlrev_b32_e32 v59, 16, v135
	v_fmac_f32_e32 v1, v20, v59
	v_sub_f32_e32 v60, 1.0, v111
	v_mul_f32_e32 v18, v18, v60
	v_fmac_f32_e32 v18, v111, v8
	global_store_dword v[52:53], v18, off offset:3584 nt
	v_and_b32_e32 v61, 0xffff0000, v135
	v_fmac_f32_e32 v1, v18, v61
	v_sub_f32_e32 v58, 1.0, v112
	v_mul_f32_e32 v16, v16, v58
	v_fmac_f32_e32 v16, v112, v8
	global_store_dword v[54:55], v16, off nt
	v_lshlrev_b32_e32 v59, 16, v136
	v_fmac_f32_e32 v1, v16, v59
	v_sub_f32_e32 v60, 1.0, v113
	v_mul_f32_e32 v14, v14, v60
	v_fmac_f32_e32 v14, v113, v8
	global_store_dword v[54:55], v14, off offset:512 nt
	v_and_b32_e32 v61, 0xffff0000, v136
	v_fmac_f32_e32 v1, v14, v61
	v_sub_f32_e32 v58, 1.0, v114
	v_mul_f32_e32 v12, v12, v58
	v_fmac_f32_e32 v12, v114, v8
	global_store_dword v[54:55], v12, off offset:1024 nt
	v_lshlrev_b32_e32 v59, 16, v137
	v_fmac_f32_e32 v1, v12, v59
	v_sub_f32_e32 v60, 1.0, v115
	v_mul_f32_e32 v9, v9, v60
	v_fmac_f32_e32 v9, v115, v8
	global_store_dword v[54:55], v9, off offset:1536 nt
	v_and_b32_e32 v61, 0xffff0000, v137
	v_fmac_f32_e32 v1, v9, v61
	v_sub_f32_e32 v58, 1.0, v116
	v_mul_f32_e32 v33, v33, v58
	v_fmac_f32_e32 v33, v116, v8
	global_store_dword v[54:55], v33, off offset:2048 nt
	v_lshlrev_b32_e32 v59, 16, v138
	v_fmac_f32_e32 v1, v33, v59
	v_sub_f32_e32 v60, 1.0, v117
	v_mul_f32_e32 v31, v31, v60
	v_fmac_f32_e32 v31, v117, v8
	global_store_dword v[54:55], v31, off offset:2560 nt
	v_and_b32_e32 v61, 0xffff0000, v138
	v_fmac_f32_e32 v1, v31, v61
	v_sub_f32_e32 v58, 1.0, v118
	v_mul_f32_e32 v29, v29, v58
	v_fmac_f32_e32 v29, v118, v8
	global_store_dword v[54:55], v29, off offset:3072 nt
	v_lshlrev_b32_e32 v59, 16, v139
	v_fmac_f32_e32 v1, v29, v59
	v_sub_f32_e32 v60, 1.0, v119
	v_mul_f32_e32 v27, v27, v60
	v_fmac_f32_e32 v27, v119, v8
	global_store_dword v[54:55], v27, off offset:3584 nt
	v_and_b32_e32 v61, 0xffff0000, v139
	v_fmac_f32_e32 v1, v27, v61
	v_sub_f32_e32 v58, 1.0, v120
	v_mul_f32_e32 v25, v25, v58
	v_fmac_f32_e32 v25, v120, v8
	global_store_dword v[56:57], v25, off nt
	v_lshlrev_b32_e32 v59, 16, v140
	v_fmac_f32_e32 v1, v25, v59
	v_sub_f32_e32 v60, 1.0, v121
	v_mul_f32_e32 v23, v23, v60
	v_fmac_f32_e32 v23, v121, v8
	global_store_dword v[56:57], v23, off offset:512 nt
	v_and_b32_e32 v61, 0xffff0000, v140
	v_fmac_f32_e32 v1, v23, v61
	v_sub_f32_e32 v58, 1.0, v122
	v_mul_f32_e32 v21, v21, v58
	v_fmac_f32_e32 v21, v122, v8
	global_store_dword v[56:57], v21, off offset:1024 nt
	v_lshlrev_b32_e32 v59, 16, v141
	v_fmac_f32_e32 v1, v21, v59
	v_sub_f32_e32 v60, 1.0, v123
	v_mul_f32_e32 v19, v19, v60
	v_fmac_f32_e32 v19, v123, v8
	global_store_dword v[56:57], v19, off offset:1536 nt
	v_and_b32_e32 v61, 0xffff0000, v141
	v_fmac_f32_e32 v1, v19, v61
	v_sub_f32_e32 v58, 1.0, v124
	v_mul_f32_e32 v17, v17, v58
	v_fmac_f32_e32 v17, v124, v8
	global_store_dword v[56:57], v17, off offset:2048 nt
	v_lshlrev_b32_e32 v59, 16, v142
	v_fmac_f32_e32 v1, v17, v59
	v_sub_f32_e32 v60, 1.0, v125
	v_mul_f32_e32 v15, v15, v60
	v_fmac_f32_e32 v15, v125, v8
	global_store_dword v[56:57], v15, off offset:2560 nt
	v_and_b32_e32 v61, 0xffff0000, v142
	v_fmac_f32_e32 v1, v15, v61
	v_sub_f32_e32 v58, 1.0, v126
	v_mul_f32_e32 v13, v13, v58
	v_fmac_f32_e32 v13, v126, v8
	global_store_dword v[56:57], v13, off offset:3072 nt
	v_lshlrev_b32_e32 v59, 16, v143
	v_fmac_f32_e32 v1, v13, v59
	v_sub_f32_e32 v60, 1.0, v127
	v_mul_f32_e32 v11, v11, v60
	v_fmac_f32_e32 v11, v127, v8
	global_store_dword v[56:57], v11, off offset:3584 nt
	v_and_b32_e32 v61, 0xffff0000, v143
	v_fmac_f32_e32 v1, v11, v61
	s_movk_i32 s0, 0x80
	v_cmp_gt_i32_e32 vcc, s0, v5
	v_lshl_add_u32 v6, v5, 2, 0
	s_barrier
	ds_write_b32 v6, v1
	s_waitcnt lgkmcnt(0)
	s_barrier
	s_and_saveexec_b64 s[10:11], vcc
	s_cbranch_execz .LBB0_325
	v_lshl_add_u32 v1, v3, 2, 0
	ds_read2st64_b32 v[6:7], v1 offset1:2
	ds_read2st64_b32 v[8:9], v1 offset0:4 offset1:6
	v_cmp_lt_i32_e64 s[0:1], v182, v181
	v_ashrrev_i32_e32 v5, 6, v5
	v_lshl_add_u32 v5, v5, 2, 0
	s_waitcnt lgkmcnt(1)
	v_mov_b32_e32 v10, v6
	s_waitcnt lgkmcnt(0)
	v_mov_b32_e32 v11, v8
	v_mov_b32_e32 v8, v7
	v_pk_add_f32 v[6:7], v[10:11], v[8:9]
	s_nop 0
	v_add_f32_e32 v1, v6, v7
	v_cndmask_b32_e64 v7, v179, v182, s[0:1]
	v_mul_f32_e32 v6, v1, v1
	v_lshlrev_b32_e32 v7, 2, v7
	ds_bpermute_b32 v6, v7, v6
	v_cmp_lt_i32_e64 s[0:1], v183, v181
	s_waitcnt lgkmcnt(0)
	v_fmac_f32_e32 v6, v1, v1
	v_cndmask_b32_e64 v7, v179, v183, s[0:1]
	v_lshlrev_b32_e32 v1, 2, v7
	ds_bpermute_b32 v1, v1, v6
	v_cmp_lt_i32_e64 s[0:1], v184, v181
	s_waitcnt lgkmcnt(0)
	v_add_f32_e32 v1, v6, v1
	v_cndmask_b32_e64 v7, v179, v184, s[0:1]
	v_lshlrev_b32_e32 v7, 2, v7
	ds_bpermute_b32 v6, v7, v1
	v_cmp_lt_i32_e64 s[0:1], v185, v181
	s_waitcnt lgkmcnt(0)
	v_add_f32_e32 v1, v1, v6
	v_cndmask_b32_e64 v7, v179, v185, s[0:1]
	v_lshlrev_b32_e32 v7, 2, v7
	ds_bpermute_b32 v6, v7, v1
	v_cmp_lt_i32_e64 s[0:1], v186, v181
	s_waitcnt lgkmcnt(0)
	v_add_f32_e32 v1, v1, v6
	v_cndmask_b32_e64 v7, v179, v186, s[0:1]
	v_lshlrev_b32_e32 v7, 2, v7
	ds_bpermute_b32 v6, v7, v1
	v_cmp_lt_i32_e64 s[0:1], v187, v181
	s_waitcnt lgkmcnt(0)
	v_add_f32_e32 v1, v1, v6
	v_cndmask_b32_e64 v7, v179, v187, s[0:1]
	v_lshlrev_b32_e32 v7, 2, v7
	ds_bpermute_b32 v6, v7, v1
	s_waitcnt lgkmcnt(0)
	v_add_f32_e32 v1, v1, v6
	ds_write_b32 v5, v1 offset:2048
.LBB0_325:
	s_or_b64 exec, exec, s[10:11]
	s_waitcnt lgkmcnt(0)
	s_barrier
	s_and_saveexec_b64 s[0:1], vcc
	s_cbranch_execz .LBB0_322
	v_add_u32_e32 v1, 0, v0
	ds_read2st64_b32 v[6:7], v1 offset1:2
	ds_read2st64_b32 v[8:9], v1 offset0:4 offset1:6
	s_waitcnt lgkmcnt(1)
	v_mov_b32_e32 v10, v6
	s_waitcnt lgkmcnt(0)
	v_mov_b32_e32 v11, v8
	v_mov_b32_e32 v8, v7
	v_pk_add_f32 v[6:7], v[10:11], v[8:9]
	s_ashr_i32 s7, s6, 31
	v_add_f32_e32 v1, v6, v7
	ds_read_b64 v[6:7], v2 offset:2048
	s_waitcnt lgkmcnt(0)
	v_add_f32_e32 v6, v6, v7
	v_fmamk_f32 v6, v6, 0x3c000000, v178
	v_cmp_gt_f32_e32 vcc, s34, v6
	v_mul_f32_e32 v7, 0x4b800000, v6
	s_nop 0
	v_cndmask_b32_e32 v6, v6, v7, vcc
	v_rsq_f32_e32 v6, v6
	s_nop 0
	v_mul_f32_e32 v7, 0x45800000, v6
	v_cndmask_b32_e32 v6, v6, v7, vcc
	v_mul_f32_e32 v8, v1, v6
	s_lshl_b64 s[6:7], s[6:7], 11
	s_add_u32 s6, s62, s6
	s_addc_u32 s7, s63, s7
	s_lshl_b32 s8, s12, 1
	s_add_u32 s6, s6, s8
	s_addc_u32 s7, s7, 0
	v_mul_f32_e32 v0, v41, v8
	v_lshlrev_b32_e32 v1, 16, v40
	v_mul_f32_e32 v0, v0, v1
	v_lshlrev_b32_e32 v1, 1, v3
	v_cvt_pk_bf16_f32 v0, v0, v2
	global_store_short v1, v0, s[6:7]
	s_branch .LBB0_322
